# ffn_up SwiGLU epilogue: packed fp32 mul/add/fma (v_pk_*_f32) for the non-transcendental steps, on top of merge A-fragment double buffering
# speedup vs baseline: 1.0024x; 1.0024x over previous
; template <int MI, int NJ> ...
;     ...
;   for (int kt = 0; kt < nk; ++kt) {
;     const int buf = kt & 1;
;     {
;       G8STORE(buf ^ 1);
;       const u16* ga_ = (kt + 2 < nk) ? Ag + (kt + 2) * 64 : Ag + nAoff;
;       const u16* gb_ = (kt + 2 < nk) ? Bg + (kt + 2) * 64 : Bg + nBoff;
;       G8LOADP(ga_, gb_);
;     }
;     __builtin_amdgcn_sched_barrier(0);
;     __builtin_amdgcn_s_setprio(1);
;     const u16* a = ra_ + buf * AROWS * 64;
;     const u16* b = rb_ + buf * BROWS * 64;
; #pragma unroll
;     for (int ks = 0; ks < 2; ++ks) {
;       const u16* a_ = ks ? a + dsw : a;
;       const u16* b_ = ks ? b + dsw : b;
;       bf16x8 bfr[NJ];
; #pragma unroll
;       for (int j = 0; j < NJ; ++j) bfr[j] = *(const bf16x8*)(b_ + j * 16 * 64);
; #pragma unroll
;       for (int ih = 0; ih < MI / 4; ++ih) {
;         bf16x8 af[4];
; #pragma unroll
;         for (int i = 0; i < 4; ++i) af[i] = *(const bf16x8*)(a_ + (ih * 4 + i) * 16 * 64);
; #pragma unroll
;         for (int i = 0; i < 4; ++i)
; #pragma unroll
;           for (int j = 0; j < NJ; ++j) acc[ih * 4 + i][j] = mfma16(af[i], bfr[j], acc[ih * 4 + i][j]);
;       }
;     }
;     __builtin_amdgcn_s_setprio(0);
;     __builtin_amdgcn_sched_barrier(0);
;     __syncthreads();
;   }
.LBB0_601:
	s_setprio 1
	s_waitcnt lgkmcnt(6)
	v_mfma_f32_16x16x32_bf16 v[158:161], v[212:215], v[208:211], v[158:161]
	s_waitcnt lgkmcnt(5)
	v_mfma_f32_16x16x32_bf16 v[154:157], v[216:219], v[208:211], v[154:157]
	s_waitcnt lgkmcnt(4)
	v_mfma_f32_16x16x32_bf16 v[150:153], v[220:223], v[208:211], v[150:153]
	s_waitcnt lgkmcnt(3)
	v_mfma_f32_16x16x32_bf16 v[146:149], v[224:227], v[208:211], v[146:149]
	ds_read_b128 v[208:211], v228 offset:8192
	s_waitcnt lgkmcnt(3)
	v_mfma_f32_16x16x32_bf16 v[142:145], v[212:215], v[234:237], v[142:145]
	v_mfma_f32_16x16x32_bf16 v[138:141], v[216:219], v[234:237], v[138:141]
	v_mfma_f32_16x16x32_bf16 v[134:137], v[220:223], v[234:237], v[134:137]
	v_mfma_f32_16x16x32_bf16 v[130:133], v[224:227], v[234:237], v[130:133]
	ds_read_b128 v[234:237], v228 offset:10240
	s_waitcnt lgkmcnt(3)
	v_mfma_f32_16x16x32_bf16 v[126:129], v[212:215], v[238:241], v[126:129]
	v_mfma_f32_16x16x32_bf16 v[122:125], v[216:219], v[238:241], v[122:125]
	v_mfma_f32_16x16x32_bf16 v[118:121], v[220:223], v[238:241], v[118:121]
	v_mfma_f32_16x16x32_bf16 v[114:117], v[224:227], v[238:241], v[114:117]
	ds_read_b128 v[238:241], v228 offset:12288
	ds_read_b128 v[242:245], v229
	ds_read_b128 v[246:249], v229 offset:2048
	s_waitcnt lgkmcnt(5)
	v_mfma_f32_16x16x32_bf16 v[110:113], v[212:215], v[204:207], v[110:113]
	v_mfma_f32_16x16x32_bf16 v[106:109], v[216:219], v[204:207], v[106:109]
	v_mfma_f32_16x16x32_bf16 v[102:105], v[220:223], v[204:207], v[102:105]
	v_mfma_f32_16x16x32_bf16 v[98:101], v[224:227], v[204:207], v[98:101]
	ds_read_b128 v[204:207], v228 offset:14336
	ds_read_b128 v[190:193], v229 offset:4096
	ds_read_b128 v[170:173], v229 offset:6144
	s_waitcnt lgkmcnt(7)
	v_mfma_f32_16x16x32_bf16 v[94:97], v[212:215], v[208:211], v[94:97]
	v_mfma_f32_16x16x32_bf16 v[90:93], v[216:219], v[208:211], v[90:93]
	v_mfma_f32_16x16x32_bf16 v[86:89], v[220:223], v[208:211], v[86:89]
	v_mfma_f32_16x16x32_bf16 v[82:85], v[224:227], v[208:211], v[82:85]
	v_add_u32_e32 v228, v228, v196
	ds_read_b128 v[208:211], v228
	s_waitcnt vmcnt(7)
	ds_write_b128 v199, v[2:5]
	global_load_dwordx4 v[2:5], v169, s[50:51]
	s_waitcnt lgkmcnt(8)
	v_mfma_f32_16x16x32_bf16 v[78:81], v[212:215], v[234:237], v[78:81]
	v_mfma_f32_16x16x32_bf16 v[74:77], v[216:219], v[234:237], v[74:77]
	v_mfma_f32_16x16x32_bf16 v[70:73], v[220:223], v[234:237], v[70:73]
	v_mfma_f32_16x16x32_bf16 v[66:69], v[224:227], v[234:237], v[66:69]
	ds_read_b128 v[234:237], v228 offset:2048
	s_waitcnt vmcnt(7)
	ds_write_b128 v199, v[6:9] offset:8192
	global_load_dwordx4 v[6:9], v194, s[50:51]
	s_waitcnt lgkmcnt(9)
	v_mfma_f32_16x16x32_bf16 v[62:65], v[212:215], v[238:241], v[62:65]
	v_mfma_f32_16x16x32_bf16 v[58:61], v[216:219], v[238:241], v[58:61]
	v_mfma_f32_16x16x32_bf16 v[54:57], v[220:223], v[238:241], v[54:57]
	v_mfma_f32_16x16x32_bf16 v[50:53], v[224:227], v[238:241], v[50:53]
	ds_read_b128 v[238:241], v228 offset:4096
	s_waitcnt vmcnt(7)
	ds_write_b128 v199, v[10:13] offset:16384
	global_load_dwordx4 v[10:13], v195, s[50:51]
	s_waitcnt lgkmcnt(8)
	v_mfma_f32_16x16x32_bf16 v[46:49], v[212:215], v[204:207], v[46:49]
	v_mfma_f32_16x16x32_bf16 v[42:45], v[216:219], v[204:207], v[42:45]
	v_mfma_f32_16x16x32_bf16 v[38:41], v[220:223], v[204:207], v[38:41]
	v_mfma_f32_16x16x32_bf16 v[34:37], v[224:227], v[204:207], v[34:37]
	ds_read_b128 v[204:207], v228 offset:6144
	s_waitcnt vmcnt(7)
	ds_write_b128 v199, v[18:21] offset:24576
	global_load_dwordx4 v[18:21], v198, s[50:51]
	s_waitcnt lgkmcnt(7)
	v_mfma_f32_16x16x32_bf16 v[158:161], v[242:245], v[208:211], v[158:161]
	v_mfma_f32_16x16x32_bf16 v[154:157], v[246:249], v[208:211], v[154:157]
	v_mfma_f32_16x16x32_bf16 v[150:153], v[190:193], v[208:211], v[150:153]
	v_mfma_f32_16x16x32_bf16 v[146:149], v[170:173], v[208:211], v[146:149]
	ds_read_b128 v[208:211], v228 offset:8192
	s_waitcnt vmcnt(7)
	ds_write_b128 v200, v[14:17]
	global_load_dwordx4 v[14:17], v169, s[52:53]
	s_waitcnt lgkmcnt(7)
	v_mfma_f32_16x16x32_bf16 v[142:145], v[242:245], v[234:237], v[142:145]
	v_mfma_f32_16x16x32_bf16 v[138:141], v[246:249], v[234:237], v[138:141]
	v_mfma_f32_16x16x32_bf16 v[134:137], v[190:193], v[234:237], v[134:137]
	v_mfma_f32_16x16x32_bf16 v[130:133], v[170:173], v[234:237], v[130:133]
	ds_read_b128 v[234:237], v228 offset:10240
	s_waitcnt vmcnt(7)
	ds_write_b128 v200, v[22:25] offset:8192
	global_load_dwordx4 v[22:25], v194, s[52:53]
	s_waitcnt lgkmcnt(7)
	v_mfma_f32_16x16x32_bf16 v[126:129], v[242:245], v[238:241], v[126:129]
	v_mfma_f32_16x16x32_bf16 v[122:125], v[246:249], v[238:241], v[122:125]
	v_mfma_f32_16x16x32_bf16 v[118:121], v[190:193], v[238:241], v[118:121]
	v_mfma_f32_16x16x32_bf16 v[114:117], v[170:173], v[238:241], v[114:117]
	ds_read_b128 v[238:241], v228 offset:12288
	s_waitcnt vmcnt(7)
	ds_write_b128 v200, v[26:29] offset:16384
	global_load_dwordx4 v[26:29], v195, s[52:53]
	s_waitcnt lgkmcnt(7)
	v_mfma_f32_16x16x32_bf16 v[110:113], v[242:245], v[204:207], v[110:113]
	v_mfma_f32_16x16x32_bf16 v[106:109], v[246:249], v[204:207], v[106:109]
	v_mfma_f32_16x16x32_bf16 v[102:105], v[190:193], v[204:207], v[102:105]
	v_mfma_f32_16x16x32_bf16 v[98:101], v[170:173], v[204:207], v[98:101]
	ds_read_b128 v[204:207], v228 offset:14336
	s_waitcnt vmcnt(7)
	ds_write_b128 v200, v[30:33] offset:24576
	global_load_dwordx4 v[30:33], v198, s[52:53]
	s_waitcnt lgkmcnt(7)
	v_mfma_f32_16x16x32_bf16 v[94:97], v[242:245], v[208:211], v[94:97]
	v_mfma_f32_16x16x32_bf16 v[90:93], v[246:249], v[208:211], v[90:93]
	v_mfma_f32_16x16x32_bf16 v[86:89], v[190:193], v[208:211], v[86:89]
	v_mfma_f32_16x16x32_bf16 v[82:85], v[170:173], v[208:211], v[82:85]
	s_waitcnt lgkmcnt(0)
	s_setprio 0
	s_barrier
; __device__ __forceinline__ float siluf_(float x) { return x / (1.0f + __expf(-x)); }
; template <int MI, int NJ> ...
;     ...
;   for (int kt = 0; kt < nk; ++kt) {
;     const int buf = kt & 1;
;     {
;       G8STORE(buf ^ 1);
;       const u16* ga_ = (kt + 2 < nk) ? Ag + (kt + 2) * 64 : Ag + nAoff;
;       const u16* gb_ = (kt + 2 < nk) ? Bg + (kt + 2) * 64 : Bg + nBoff;
;       G8LOADP(ga_, gb_);
;     }
;     __builtin_amdgcn_sched_barrier(0);
;     __builtin_amdgcn_s_setprio(1);
;     const u16* a = ra_ + buf * AROWS * 64;
;     const u16* b = rb_ + buf * BROWS * 64;
; #pragma unroll
;     for (int ks = 0; ks < 2; ++ks) {
;       const u16* a_ = ks ? a + dsw : a;
;       const u16* b_ = ks ? b + dsw : b;
;       bf16x8 bfr[NJ];
; #pragma unroll
;       for (int j = 0; j < NJ; ++j) bfr[j] = *(const bf16x8*)(b_ + j * 16 * 64);
; #pragma unroll
;       for (int ih = 0; ih < MI / 4; ++ih) {
;         bf16x8 af[4];
; #pragma unroll
;         for (int i = 0; i < 4; ++i) af[i] = *(const bf16x8*)(a_ + (ih * 4 + i) * 16 * 64);
; #pragma unroll
;         for (int i = 0; i < 4; ++i)
; #pragma unroll
;           for (int j = 0; j < NJ; ++j) acc[ih * 4 + i][j] = mfma16(af[i], bfr[j], acc[ih * 4 + i][j]);
;       }
;     }
;     __builtin_amdgcn_s_setprio(0);
;     __builtin_amdgcn_sched_barrier(0);
;     __syncthreads();
;   }
; __device__ __forceinline__ void phase_ffn_up(const Params& p, const u16* Wgu, u16* smem, volatile LAS unsigned* vb_) {
;     ...
; #pragma unroll
;     for (int i = 0; i < 8; ++i)
; #pragma unroll
;       for (int jp = 0; jp < 2; ++jp) {
; #pragma unroll
;         for (int r = 0; r < 4; ++r) {
;           const float g = acc[i][2 * jp][r], u = acc[i][2 * jp + 1][r];
;           smem[(wm * 128 + i * 16 + (lane >> 4) * 4 + r) * 136 + (wn * 2 + jp) * 16 + (lane & 15)] = f2bf(siluf_(g) * u);
;         }
;         __builtin_amdgcn_sched_barrier(0);
;       }
	s_add_i32 s43, s43, 1
	s_add_u32 s22, s22, 64
	s_addc_u32 s23, s23, 0
	s_addk_i32 s42, 0x4000
	s_and_b32 s48, s42, 0x4000
	s_xor_b32 s44, s48, 0x4000
	s_lshl_b32 s44, s44, 1
	v_add_u32_e32 v199, s44, v185
	v_add_u32_e32 v200, s44, v186
	s_cmp_lt_u32 s43, 14
	s_cselect_b32 s45, s23, s13
	s_cselect_b32 s44, s22, s12
	s_cselect_b32 s47, s23, s21
	s_cselect_b32 s46, s22, s20
	s_lshl_b64 s[44:45], s[44:45], 1
	s_lshl_b64 s[46:47], s[46:47], 1
	s_add_u32 s50, s62, s44
	s_addc_u32 s51, s63, s45
	s_add_u32 s52, s64, s46
	s_addc_u32 s53, s65, s47
	s_lshl_b32 s44, s48, 1
	v_add_u32_e32 v228, s44, v187
	v_add_u32_e32 v229, s44, v188
	s_setprio 1
	ds_read_b128 v[212:215], v229
	ds_read_b128 v[208:211], v228
	ds_read_b128 v[216:219], v229 offset:2048
	ds_read_b128 v[220:223], v229 offset:4096
	ds_read_b128 v[224:227], v229 offset:6144
	v_mfma_f32_16x16x32_bf16 v[78:81], v[242:245], v[234:237], v[78:81]
	v_mfma_f32_16x16x32_bf16 v[74:77], v[246:249], v[234:237], v[74:77]
	v_mfma_f32_16x16x32_bf16 v[70:73], v[190:193], v[234:237], v[70:73]
	v_mfma_f32_16x16x32_bf16 v[66:69], v[170:173], v[234:237], v[66:69]
	ds_read_b128 v[234:237], v228 offset:2048
	v_mfma_f32_16x16x32_bf16 v[62:65], v[242:245], v[238:241], v[62:65]
	v_mfma_f32_16x16x32_bf16 v[58:61], v[246:249], v[238:241], v[58:61]
	v_mfma_f32_16x16x32_bf16 v[54:57], v[190:193], v[238:241], v[54:57]
	v_mfma_f32_16x16x32_bf16 v[50:53], v[170:173], v[238:241], v[50:53]
	ds_read_b128 v[238:241], v228 offset:4096
	v_mfma_f32_16x16x32_bf16 v[46:49], v[242:245], v[204:207], v[46:49]
	v_mfma_f32_16x16x32_bf16 v[42:45], v[246:249], v[204:207], v[42:45]
	v_mfma_f32_16x16x32_bf16 v[38:41], v[190:193], v[204:207], v[38:41]
	v_mfma_f32_16x16x32_bf16 v[34:37], v[170:173], v[204:207], v[34:37]
	ds_read_b128 v[204:207], v228 offset:6144
	v_add_u32_e32 v229, v229, v196
	s_setprio 0
	s_cmpk_lg_i32 s22, 0x480
	s_cbranch_scc1 .LBB0_601
	v_and_b32_e32 v228, 15, v175
	v_bfe_u32 v229, v175, 8, 1
	v_lshl_or_b32 v228, v229, 7, v228
	v_mul_u32_u24_e32 v228, 0x110, v228
	v_bfe_u32 v229, v175, 6, 2
	v_lshl_add_u32 v228, v229, 6, v228
	v_bfe_u32 v229, v175, 4, 2
	v_lshl_add_u32 v228, v229, 3, v228
	v_mov_b32_e32 v224, 0xbfb8aa3b
	v_mov_b32_e32 v226, 1.0
	v_pk_mul_f32 v[208:209], v[158:159], v[224:225] op_sel_hi:[1,0]
	v_pk_mul_f32 v[210:211], v[160:161], v[224:225] op_sel_hi:[1,0]
	v_pk_mul_f32 v[212:213], v[150:151], v[224:225] op_sel_hi:[1,0]
	v_pk_mul_f32 v[214:215], v[152:153], v[224:225] op_sel_hi:[1,0]
	v_min_f32_e32 v208, 0x42fc0000, v208
	v_min_f32_e32 v209, 0x42fc0000, v209
	v_min_f32_e32 v210, 0x42fc0000, v210
	v_min_f32_e32 v211, 0x42fc0000, v211
	v_min_f32_e32 v212, 0x42fc0000, v212
	v_min_f32_e32 v213, 0x42fc0000, v213
	v_min_f32_e32 v214, 0x42fc0000, v214
	v_min_f32_e32 v215, 0x42fc0000, v215
	v_exp_f32_e32 v208, v208
	v_exp_f32_e32 v209, v209
	v_exp_f32_e32 v210, v210
	v_exp_f32_e32 v211, v211
	v_exp_f32_e32 v212, v212
	v_exp_f32_e32 v213, v213
	v_exp_f32_e32 v214, v214
	v_exp_f32_e32 v215, v215
	v_pk_add_f32 v[208:209], v[208:209], v[226:227] op_sel_hi:[1,0]
	v_pk_add_f32 v[210:211], v[210:211], v[226:227] op_sel_hi:[1,0]
	v_pk_add_f32 v[212:213], v[212:213], v[226:227] op_sel_hi:[1,0]
	v_pk_add_f32 v[214:215], v[214:215], v[226:227] op_sel_hi:[1,0]
	v_rcp_f32_e32 v216, v208
	v_rcp_f32_e32 v217, v209
	v_rcp_f32_e32 v218, v210
	v_rcp_f32_e32 v219, v211
	v_rcp_f32_e32 v220, v212
	v_rcp_f32_e32 v221, v213
	v_rcp_f32_e32 v222, v214
	v_rcp_f32_e32 v223, v215
	v_pk_fma_f32 v[208:209], v[208:209], v[216:217], v[226:227] op_sel_hi:[1,1,0] neg_lo:[1,0,0] neg_hi:[1,0,0]
	v_pk_fma_f32 v[210:211], v[210:211], v[218:219], v[226:227] op_sel_hi:[1,1,0] neg_lo:[1,0,0] neg_hi:[1,0,0]
	v_pk_fma_f32 v[212:213], v[212:213], v[220:221], v[226:227] op_sel_hi:[1,1,0] neg_lo:[1,0,0] neg_hi:[1,0,0]
	v_pk_fma_f32 v[214:215], v[214:215], v[222:223], v[226:227] op_sel_hi:[1,1,0] neg_lo:[1,0,0] neg_hi:[1,0,0]
	v_pk_fma_f32 v[216:217], v[208:209], v[216:217], v[216:217]
	v_pk_fma_f32 v[218:219], v[210:211], v[218:219], v[218:219]
	v_pk_fma_f32 v[220:221], v[212:213], v[220:221], v[220:221]
	v_pk_fma_f32 v[222:223], v[214:215], v[222:223], v[222:223]
	v_pk_mul_f32 v[158:159], v[158:159], v[216:217]
	v_pk_mul_f32 v[160:161], v[160:161], v[218:219]
	v_pk_mul_f32 v[150:151], v[150:151], v[220:221]
	v_pk_mul_f32 v[152:153], v[152:153], v[222:223]
	v_pk_mul_f32 v[158:159], v[158:159], v[154:155]
	v_pk_mul_f32 v[160:161], v[160:161], v[156:157]
	v_pk_mul_f32 v[150:151], v[150:151], v[146:147]
	v_pk_mul_f32 v[152:153], v[152:153], v[148:149]
	v_cvt_pk_bf16_f32 v158, v158, v159
	v_cvt_pk_bf16_f32 v159, v160, v161
	v_cvt_pk_bf16_f32 v150, v150, v151
	v_cvt_pk_bf16_f32 v151, v152, v153
	ds_write_b64 v228, v[158:159]
	ds_write_b64 v228, v[150:151] offset:32
	v_pk_mul_f32 v[208:209], v[142:143], v[224:225] op_sel_hi:[1,0]
	v_pk_mul_f32 v[210:211], v[144:145], v[224:225] op_sel_hi:[1,0]
	v_pk_mul_f32 v[212:213], v[134:135], v[224:225] op_sel_hi:[1,0]
	v_pk_mul_f32 v[214:215], v[136:137], v[224:225] op_sel_hi:[1,0]
	v_min_f32_e32 v208, 0x42fc0000, v208
	v_min_f32_e32 v209, 0x42fc0000, v209
	v_min_f32_e32 v210, 0x42fc0000, v210
	v_min_f32_e32 v211, 0x42fc0000, v211
	v_min_f32_e32 v212, 0x42fc0000, v212
	v_min_f32_e32 v213, 0x42fc0000, v213
	v_min_f32_e32 v214, 0x42fc0000, v214
	v_min_f32_e32 v215, 0x42fc0000, v215
	v_exp_f32_e32 v208, v208
	v_exp_f32_e32 v209, v209
	v_exp_f32_e32 v210, v210
	v_exp_f32_e32 v211, v211
	v_exp_f32_e32 v212, v212
	v_exp_f32_e32 v213, v213
	v_exp_f32_e32 v214, v214
	v_exp_f32_e32 v215, v215
	v_pk_add_f32 v[208:209], v[208:209], v[226:227] op_sel_hi:[1,0]
	v_pk_add_f32 v[210:211], v[210:211], v[226:227] op_sel_hi:[1,0]
; __device__ __forceinline__ float siluf_(float x) { return x / (1.0f + __expf(-x)); }
; __device__ __forceinline__ void phase_ffn_up(const Params& p, const u16* Wgu, u16* smem, volatile LAS unsigned* vb_) {
;     ...
; #pragma unroll
;     for (int i = 0; i < 8; ++i)
; #pragma unroll
;       for (int jp = 0; jp < 2; ++jp) {
; #pragma unroll
;         for (int r = 0; r < 4; ++r) {
;           const float g = acc[i][2 * jp][r], u = acc[i][2 * jp + 1][r];
;           smem[(wm * 128 + i * 16 + (lane >> 4) * 4 + r) * 136 + (wn * 2 + jp) * 16 + (lane & 15)] = f2bf(siluf_(g) * u);
;         }
;         __builtin_amdgcn_sched_barrier(0);
;       }
	v_pk_add_f32 v[212:213], v[212:213], v[226:227] op_sel_hi:[1,0]
	v_pk_add_f32 v[214:215], v[214:215], v[226:227] op_sel_hi:[1,0]
	v_rcp_f32_e32 v216, v208
	v_rcp_f32_e32 v217, v209
	v_rcp_f32_e32 v218, v210
	v_rcp_f32_e32 v219, v211
	v_rcp_f32_e32 v220, v212
	v_rcp_f32_e32 v221, v213
	v_rcp_f32_e32 v222, v214
	v_rcp_f32_e32 v223, v215
	v_pk_fma_f32 v[208:209], v[208:209], v[216:217], v[226:227] op_sel_hi:[1,1,0] neg_lo:[1,0,0] neg_hi:[1,0,0]
	v_pk_fma_f32 v[210:211], v[210:211], v[218:219], v[226:227] op_sel_hi:[1,1,0] neg_lo:[1,0,0] neg_hi:[1,0,0]
	v_pk_fma_f32 v[212:213], v[212:213], v[220:221], v[226:227] op_sel_hi:[1,1,0] neg_lo:[1,0,0] neg_hi:[1,0,0]
	v_pk_fma_f32 v[214:215], v[214:215], v[222:223], v[226:227] op_sel_hi:[1,1,0] neg_lo:[1,0,0] neg_hi:[1,0,0]
	v_pk_fma_f32 v[216:217], v[208:209], v[216:217], v[216:217]
	v_pk_fma_f32 v[218:219], v[210:211], v[218:219], v[218:219]
	v_pk_fma_f32 v[220:221], v[212:213], v[220:221], v[220:221]
	v_pk_fma_f32 v[222:223], v[214:215], v[222:223], v[222:223]
	v_pk_mul_f32 v[142:143], v[142:143], v[216:217]
	v_pk_mul_f32 v[144:145], v[144:145], v[218:219]
	v_pk_mul_f32 v[134:135], v[134:135], v[220:221]
	v_pk_mul_f32 v[136:137], v[136:137], v[222:223]
	v_pk_mul_f32 v[142:143], v[142:143], v[138:139]
	v_pk_mul_f32 v[144:145], v[144:145], v[140:141]
	v_pk_mul_f32 v[134:135], v[134:135], v[130:131]
	v_pk_mul_f32 v[136:137], v[136:137], v[132:133]
	v_cvt_pk_bf16_f32 v142, v142, v143
	v_cvt_pk_bf16_f32 v143, v144, v145
	v_cvt_pk_bf16_f32 v134, v134, v135
	v_cvt_pk_bf16_f32 v135, v136, v137
	ds_write_b64 v228, v[142:143] offset:4352
	ds_write_b64 v228, v[134:135] offset:4384
	v_pk_mul_f32 v[208:209], v[126:127], v[224:225] op_sel_hi:[1,0]
	v_pk_mul_f32 v[210:211], v[128:129], v[224:225] op_sel_hi:[1,0]
	v_pk_mul_f32 v[212:213], v[118:119], v[224:225] op_sel_hi:[1,0]
	v_pk_mul_f32 v[214:215], v[120:121], v[224:225] op_sel_hi:[1,0]
	v_min_f32_e32 v208, 0x42fc0000, v208
	v_min_f32_e32 v209, 0x42fc0000, v209
	v_min_f32_e32 v210, 0x42fc0000, v210
	v_min_f32_e32 v211, 0x42fc0000, v211
	v_min_f32_e32 v212, 0x42fc0000, v212
	v_min_f32_e32 v213, 0x42fc0000, v213
	v_min_f32_e32 v214, 0x42fc0000, v214
	v_min_f32_e32 v215, 0x42fc0000, v215
	v_exp_f32_e32 v208, v208
	v_exp_f32_e32 v209, v209
	v_exp_f32_e32 v210, v210
	v_exp_f32_e32 v211, v211
	v_exp_f32_e32 v212, v212
	v_exp_f32_e32 v213, v213
	v_exp_f32_e32 v214, v214
	v_exp_f32_e32 v215, v215
	v_pk_add_f32 v[208:209], v[208:209], v[226:227] op_sel_hi:[1,0]
	v_pk_add_f32 v[210:211], v[210:211], v[226:227] op_sel_hi:[1,0]
	v_pk_add_f32 v[212:213], v[212:213], v[226:227] op_sel_hi:[1,0]
	v_pk_add_f32 v[214:215], v[214:215], v[226:227] op_sel_hi:[1,0]
	v_rcp_f32_e32 v216, v208
	v_rcp_f32_e32 v217, v209
	v_rcp_f32_e32 v218, v210
	v_rcp_f32_e32 v219, v211
	v_rcp_f32_e32 v220, v212
	v_rcp_f32_e32 v221, v213
	v_rcp_f32_e32 v222, v214
	v_rcp_f32_e32 v223, v215
	v_pk_fma_f32 v[208:209], v[208:209], v[216:217], v[226:227] op_sel_hi:[1,1,0] neg_lo:[1,0,0] neg_hi:[1,0,0]
	v_pk_fma_f32 v[210:211], v[210:211], v[218:219], v[226:227] op_sel_hi:[1,1,0] neg_lo:[1,0,0] neg_hi:[1,0,0]
	v_pk_fma_f32 v[212:213], v[212:213], v[220:221], v[226:227] op_sel_hi:[1,1,0] neg_lo:[1,0,0] neg_hi:[1,0,0]
	v_pk_fma_f32 v[214:215], v[214:215], v[222:223], v[226:227] op_sel_hi:[1,1,0] neg_lo:[1,0,0] neg_hi:[1,0,0]
	v_pk_fma_f32 v[216:217], v[208:209], v[216:217], v[216:217]
	v_pk_fma_f32 v[218:219], v[210:211], v[218:219], v[218:219]
	v_pk_fma_f32 v[220:221], v[212:213], v[220:221], v[220:221]
	v_pk_fma_f32 v[222:223], v[214:215], v[222:223], v[222:223]
	v_pk_mul_f32 v[126:127], v[126:127], v[216:217]
	v_pk_mul_f32 v[128:129], v[128:129], v[218:219]
	v_pk_mul_f32 v[118:119], v[118:119], v[220:221]
	v_pk_mul_f32 v[120:121], v[120:121], v[222:223]
	v_pk_mul_f32 v[126:127], v[126:127], v[122:123]
	v_pk_mul_f32 v[128:129], v[128:129], v[124:125]
	v_pk_mul_f32 v[118:119], v[118:119], v[114:115]
	v_pk_mul_f32 v[120:121], v[120:121], v[116:117]
	v_cvt_pk_bf16_f32 v126, v126, v127
	v_cvt_pk_bf16_f32 v127, v128, v129
	v_cvt_pk_bf16_f32 v118, v118, v119
	v_cvt_pk_bf16_f32 v119, v120, v121
	ds_write_b64 v228, v[126:127] offset:8704
	ds_write_b64 v228, v[118:119] offset:8736
	v_pk_mul_f32 v[208:209], v[110:111], v[224:225] op_sel_hi:[1,0]
	v_pk_mul_f32 v[210:211], v[112:113], v[224:225] op_sel_hi:[1,0]
	v_pk_mul_f32 v[212:213], v[102:103], v[224:225] op_sel_hi:[1,0]
	v_pk_mul_f32 v[214:215], v[104:105], v[224:225] op_sel_hi:[1,0]
	v_min_f32_e32 v208, 0x42fc0000, v208
	v_min_f32_e32 v209, 0x42fc0000, v209
	v_min_f32_e32 v210, 0x42fc0000, v210
	v_min_f32_e32 v211, 0x42fc0000, v211
	v_min_f32_e32 v212, 0x42fc0000, v212
	v_min_f32_e32 v213, 0x42fc0000, v213
	v_min_f32_e32 v214, 0x42fc0000, v214
	v_min_f32_e32 v215, 0x42fc0000, v215
	v_exp_f32_e32 v208, v208
	v_exp_f32_e32 v209, v209
	v_exp_f32_e32 v210, v210
	v_exp_f32_e32 v211, v211
	v_exp_f32_e32 v212, v212
	v_exp_f32_e32 v213, v213
	v_exp_f32_e32 v214, v214
	v_exp_f32_e32 v215, v215
	v_pk_add_f32 v[208:209], v[208:209], v[226:227] op_sel_hi:[1,0]
	v_pk_add_f32 v[210:211], v[210:211], v[226:227] op_sel_hi:[1,0]
	v_pk_add_f32 v[212:213], v[212:213], v[226:227] op_sel_hi:[1,0]
	v_pk_add_f32 v[214:215], v[214:215], v[226:227] op_sel_hi:[1,0]
	v_rcp_f32_e32 v216, v208
	v_rcp_f32_e32 v217, v209
	v_rcp_f32_e32 v218, v210
	v_rcp_f32_e32 v219, v211
	v_rcp_f32_e32 v220, v212
	v_rcp_f32_e32 v221, v213
	v_rcp_f32_e32 v222, v214
	v_rcp_f32_e32 v223, v215
	v_pk_fma_f32 v[208:209], v[208:209], v[216:217], v[226:227] op_sel_hi:[1,1,0] neg_lo:[1,0,0] neg_hi:[1,0,0]
	v_pk_fma_f32 v[210:211], v[210:211], v[218:219], v[226:227] op_sel_hi:[1,1,0] neg_lo:[1,0,0] neg_hi:[1,0,0]
; __device__ __forceinline__ float siluf_(float x) { return x / (1.0f + __expf(-x)); }
; __device__ __forceinline__ void phase_ffn_up(const Params& p, const u16* Wgu, u16* smem, volatile LAS unsigned* vb_) {
;     ...
; #pragma unroll
;     for (int i = 0; i < 8; ++i)
; #pragma unroll
;       for (int jp = 0; jp < 2; ++jp) {
; #pragma unroll
;         for (int r = 0; r < 4; ++r) {
;           const float g = acc[i][2 * jp][r], u = acc[i][2 * jp + 1][r];
;           smem[(wm * 128 + i * 16 + (lane >> 4) * 4 + r) * 136 + (wn * 2 + jp) * 16 + (lane & 15)] = f2bf(siluf_(g) * u);
;         }
;         __builtin_amdgcn_sched_barrier(0);
;       }
	v_pk_fma_f32 v[212:213], v[212:213], v[220:221], v[226:227] op_sel_hi:[1,1,0] neg_lo:[1,0,0] neg_hi:[1,0,0]
	v_pk_fma_f32 v[214:215], v[214:215], v[222:223], v[226:227] op_sel_hi:[1,1,0] neg_lo:[1,0,0] neg_hi:[1,0,0]
	v_pk_fma_f32 v[216:217], v[208:209], v[216:217], v[216:217]
	v_pk_fma_f32 v[218:219], v[210:211], v[218:219], v[218:219]
	v_pk_fma_f32 v[220:221], v[212:213], v[220:221], v[220:221]
	v_pk_fma_f32 v[222:223], v[214:215], v[222:223], v[222:223]
	v_pk_mul_f32 v[110:111], v[110:111], v[216:217]
	v_pk_mul_f32 v[112:113], v[112:113], v[218:219]
	v_pk_mul_f32 v[102:103], v[102:103], v[220:221]
	v_pk_mul_f32 v[104:105], v[104:105], v[222:223]
	v_pk_mul_f32 v[110:111], v[110:111], v[106:107]
	v_pk_mul_f32 v[112:113], v[112:113], v[108:109]
	v_pk_mul_f32 v[102:103], v[102:103], v[98:99]
	v_pk_mul_f32 v[104:105], v[104:105], v[100:101]
	v_cvt_pk_bf16_f32 v110, v110, v111
	v_cvt_pk_bf16_f32 v111, v112, v113
	v_cvt_pk_bf16_f32 v102, v102, v103
	v_cvt_pk_bf16_f32 v103, v104, v105
	ds_write_b64 v228, v[110:111] offset:13056
	ds_write_b64 v228, v[102:103] offset:13088
	v_pk_mul_f32 v[208:209], v[94:95], v[224:225] op_sel_hi:[1,0]
	v_pk_mul_f32 v[210:211], v[96:97], v[224:225] op_sel_hi:[1,0]
	v_pk_mul_f32 v[212:213], v[86:87], v[224:225] op_sel_hi:[1,0]
	v_pk_mul_f32 v[214:215], v[88:89], v[224:225] op_sel_hi:[1,0]
	v_min_f32_e32 v208, 0x42fc0000, v208
	v_min_f32_e32 v209, 0x42fc0000, v209
	v_min_f32_e32 v210, 0x42fc0000, v210
	v_min_f32_e32 v211, 0x42fc0000, v211
	v_min_f32_e32 v212, 0x42fc0000, v212
	v_min_f32_e32 v213, 0x42fc0000, v213
	v_min_f32_e32 v214, 0x42fc0000, v214
	v_min_f32_e32 v215, 0x42fc0000, v215
	v_exp_f32_e32 v208, v208
	v_exp_f32_e32 v209, v209
	v_exp_f32_e32 v210, v210
	v_exp_f32_e32 v211, v211
	v_exp_f32_e32 v212, v212
	v_exp_f32_e32 v213, v213
	v_exp_f32_e32 v214, v214
	v_exp_f32_e32 v215, v215
	v_pk_add_f32 v[208:209], v[208:209], v[226:227] op_sel_hi:[1,0]
	v_pk_add_f32 v[210:211], v[210:211], v[226:227] op_sel_hi:[1,0]
	v_pk_add_f32 v[212:213], v[212:213], v[226:227] op_sel_hi:[1,0]
	v_pk_add_f32 v[214:215], v[214:215], v[226:227] op_sel_hi:[1,0]
	v_rcp_f32_e32 v216, v208
	v_rcp_f32_e32 v217, v209
	v_rcp_f32_e32 v218, v210
	v_rcp_f32_e32 v219, v211
	v_rcp_f32_e32 v220, v212
	v_rcp_f32_e32 v221, v213
	v_rcp_f32_e32 v222, v214
	v_rcp_f32_e32 v223, v215
	v_pk_fma_f32 v[208:209], v[208:209], v[216:217], v[226:227] op_sel_hi:[1,1,0] neg_lo:[1,0,0] neg_hi:[1,0,0]
	v_pk_fma_f32 v[210:211], v[210:211], v[218:219], v[226:227] op_sel_hi:[1,1,0] neg_lo:[1,0,0] neg_hi:[1,0,0]
	v_pk_fma_f32 v[212:213], v[212:213], v[220:221], v[226:227] op_sel_hi:[1,1,0] neg_lo:[1,0,0] neg_hi:[1,0,0]
	v_pk_fma_f32 v[214:215], v[214:215], v[222:223], v[226:227] op_sel_hi:[1,1,0] neg_lo:[1,0,0] neg_hi:[1,0,0]
	v_pk_fma_f32 v[216:217], v[208:209], v[216:217], v[216:217]
	v_pk_fma_f32 v[218:219], v[210:211], v[218:219], v[218:219]
	v_pk_fma_f32 v[220:221], v[212:213], v[220:221], v[220:221]
	v_pk_fma_f32 v[222:223], v[214:215], v[222:223], v[222:223]
	v_pk_mul_f32 v[94:95], v[94:95], v[216:217]
	v_pk_mul_f32 v[96:97], v[96:97], v[218:219]
	v_pk_mul_f32 v[86:87], v[86:87], v[220:221]
	v_pk_mul_f32 v[88:89], v[88:89], v[222:223]
	v_pk_mul_f32 v[94:95], v[94:95], v[90:91]
	v_pk_mul_f32 v[96:97], v[96:97], v[92:93]
	v_pk_mul_f32 v[86:87], v[86:87], v[82:83]
	v_pk_mul_f32 v[88:89], v[88:89], v[84:85]
	v_cvt_pk_bf16_f32 v94, v94, v95
	v_cvt_pk_bf16_f32 v95, v96, v97
	v_cvt_pk_bf16_f32 v86, v86, v87
	v_cvt_pk_bf16_f32 v87, v88, v89
	ds_write_b64 v228, v[94:95] offset:17408
	ds_write_b64 v228, v[86:87] offset:17440
	v_pk_mul_f32 v[208:209], v[78:79], v[224:225] op_sel_hi:[1,0]
	v_pk_mul_f32 v[210:211], v[80:81], v[224:225] op_sel_hi:[1,0]
	v_pk_mul_f32 v[212:213], v[70:71], v[224:225] op_sel_hi:[1,0]
	v_pk_mul_f32 v[214:215], v[72:73], v[224:225] op_sel_hi:[1,0]
	v_min_f32_e32 v208, 0x42fc0000, v208
	v_min_f32_e32 v209, 0x42fc0000, v209
	v_min_f32_e32 v210, 0x42fc0000, v210
	v_min_f32_e32 v211, 0x42fc0000, v211
	v_min_f32_e32 v212, 0x42fc0000, v212
	v_min_f32_e32 v213, 0x42fc0000, v213
	v_min_f32_e32 v214, 0x42fc0000, v214
	v_min_f32_e32 v215, 0x42fc0000, v215
	v_exp_f32_e32 v208, v208
	v_exp_f32_e32 v209, v209
	v_exp_f32_e32 v210, v210
	v_exp_f32_e32 v211, v211
	v_exp_f32_e32 v212, v212
	v_exp_f32_e32 v213, v213
	v_exp_f32_e32 v214, v214
	v_exp_f32_e32 v215, v215
	v_pk_add_f32 v[208:209], v[208:209], v[226:227] op_sel_hi:[1,0]
	v_pk_add_f32 v[210:211], v[210:211], v[226:227] op_sel_hi:[1,0]
	v_pk_add_f32 v[212:213], v[212:213], v[226:227] op_sel_hi:[1,0]
	v_pk_add_f32 v[214:215], v[214:215], v[226:227] op_sel_hi:[1,0]
	v_rcp_f32_e32 v216, v208
	v_rcp_f32_e32 v217, v209
	v_rcp_f32_e32 v218, v210
	v_rcp_f32_e32 v219, v211
	v_rcp_f32_e32 v220, v212
	v_rcp_f32_e32 v221, v213
	v_rcp_f32_e32 v222, v214
	v_rcp_f32_e32 v223, v215
	v_pk_fma_f32 v[208:209], v[208:209], v[216:217], v[226:227] op_sel_hi:[1,1,0] neg_lo:[1,0,0] neg_hi:[1,0,0]
	v_pk_fma_f32 v[210:211], v[210:211], v[218:219], v[226:227] op_sel_hi:[1,1,0] neg_lo:[1,0,0] neg_hi:[1,0,0]
	v_pk_fma_f32 v[212:213], v[212:213], v[220:221], v[226:227] op_sel_hi:[1,1,0] neg_lo:[1,0,0] neg_hi:[1,0,0]
	v_pk_fma_f32 v[214:215], v[214:215], v[222:223], v[226:227] op_sel_hi:[1,1,0] neg_lo:[1,0,0] neg_hi:[1,0,0]
	v_pk_fma_f32 v[216:217], v[208:209], v[216:217], v[216:217]
	v_pk_fma_f32 v[218:219], v[210:211], v[218:219], v[218:219]
	v_pk_fma_f32 v[220:221], v[212:213], v[220:221], v[220:221]
	v_pk_fma_f32 v[222:223], v[214:215], v[222:223], v[222:223]
	v_pk_mul_f32 v[78:79], v[78:79], v[216:217]
	v_pk_mul_f32 v[80:81], v[80:81], v[218:219]
	v_pk_mul_f32 v[70:71], v[70:71], v[220:221]
	v_pk_mul_f32 v[72:73], v[72:73], v[222:223]
; __device__ __forceinline__ float siluf_(float x) { return x / (1.0f + __expf(-x)); }
; __device__ __forceinline__ void phase_ffn_up(const Params& p, const u16* Wgu, u16* smem, volatile LAS unsigned* vb_) {
;     ...
; #pragma unroll
;     for (int i = 0; i < 8; ++i)
; #pragma unroll
;       for (int jp = 0; jp < 2; ++jp) {
; #pragma unroll
;         for (int r = 0; r < 4; ++r) {
;           const float g = acc[i][2 * jp][r], u = acc[i][2 * jp + 1][r];
;           smem[(wm * 128 + i * 16 + (lane >> 4) * 4 + r) * 136 + (wn * 2 + jp) * 16 + (lane & 15)] = f2bf(siluf_(g) * u);
;         }
;         __builtin_amdgcn_sched_barrier(0);
;       }
;     __syncthreads();
	v_pk_mul_f32 v[78:79], v[78:79], v[74:75]
	v_pk_mul_f32 v[80:81], v[80:81], v[76:77]
	v_pk_mul_f32 v[70:71], v[70:71], v[66:67]
	v_pk_mul_f32 v[72:73], v[72:73], v[68:69]
	v_cvt_pk_bf16_f32 v78, v78, v79
	v_cvt_pk_bf16_f32 v79, v80, v81
	v_cvt_pk_bf16_f32 v70, v70, v71
	v_cvt_pk_bf16_f32 v71, v72, v73
	ds_write_b64 v228, v[78:79] offset:21760
	ds_write_b64 v228, v[70:71] offset:21792
	v_pk_mul_f32 v[208:209], v[62:63], v[224:225] op_sel_hi:[1,0]
	v_pk_mul_f32 v[210:211], v[64:65], v[224:225] op_sel_hi:[1,0]
	v_pk_mul_f32 v[212:213], v[54:55], v[224:225] op_sel_hi:[1,0]
	v_pk_mul_f32 v[214:215], v[56:57], v[224:225] op_sel_hi:[1,0]
	v_min_f32_e32 v208, 0x42fc0000, v208
	v_min_f32_e32 v209, 0x42fc0000, v209
	v_min_f32_e32 v210, 0x42fc0000, v210
	v_min_f32_e32 v211, 0x42fc0000, v211
	v_min_f32_e32 v212, 0x42fc0000, v212
	v_min_f32_e32 v213, 0x42fc0000, v213
	v_min_f32_e32 v214, 0x42fc0000, v214
	v_min_f32_e32 v215, 0x42fc0000, v215
	v_exp_f32_e32 v208, v208
	v_exp_f32_e32 v209, v209
	v_exp_f32_e32 v210, v210
	v_exp_f32_e32 v211, v211
	v_exp_f32_e32 v212, v212
	v_exp_f32_e32 v213, v213
	v_exp_f32_e32 v214, v214
	v_exp_f32_e32 v215, v215
	v_pk_add_f32 v[208:209], v[208:209], v[226:227] op_sel_hi:[1,0]
	v_pk_add_f32 v[210:211], v[210:211], v[226:227] op_sel_hi:[1,0]
	v_pk_add_f32 v[212:213], v[212:213], v[226:227] op_sel_hi:[1,0]
	v_pk_add_f32 v[214:215], v[214:215], v[226:227] op_sel_hi:[1,0]
	v_rcp_f32_e32 v216, v208
	v_rcp_f32_e32 v217, v209
	v_rcp_f32_e32 v218, v210
	v_rcp_f32_e32 v219, v211
	v_rcp_f32_e32 v220, v212
	v_rcp_f32_e32 v221, v213
	v_rcp_f32_e32 v222, v214
	v_rcp_f32_e32 v223, v215
	v_pk_fma_f32 v[208:209], v[208:209], v[216:217], v[226:227] op_sel_hi:[1,1,0] neg_lo:[1,0,0] neg_hi:[1,0,0]
	v_pk_fma_f32 v[210:211], v[210:211], v[218:219], v[226:227] op_sel_hi:[1,1,0] neg_lo:[1,0,0] neg_hi:[1,0,0]
	v_pk_fma_f32 v[212:213], v[212:213], v[220:221], v[226:227] op_sel_hi:[1,1,0] neg_lo:[1,0,0] neg_hi:[1,0,0]
	v_pk_fma_f32 v[214:215], v[214:215], v[222:223], v[226:227] op_sel_hi:[1,1,0] neg_lo:[1,0,0] neg_hi:[1,0,0]
	v_pk_fma_f32 v[216:217], v[208:209], v[216:217], v[216:217]
	v_pk_fma_f32 v[218:219], v[210:211], v[218:219], v[218:219]
	v_pk_fma_f32 v[220:221], v[212:213], v[220:221], v[220:221]
	v_pk_fma_f32 v[222:223], v[214:215], v[222:223], v[222:223]
	v_pk_mul_f32 v[62:63], v[62:63], v[216:217]
	v_pk_mul_f32 v[64:65], v[64:65], v[218:219]
	v_pk_mul_f32 v[54:55], v[54:55], v[220:221]
	v_pk_mul_f32 v[56:57], v[56:57], v[222:223]
	v_pk_mul_f32 v[62:63], v[62:63], v[58:59]
	v_pk_mul_f32 v[64:65], v[64:65], v[60:61]
	v_pk_mul_f32 v[54:55], v[54:55], v[50:51]
	v_pk_mul_f32 v[56:57], v[56:57], v[52:53]
	v_cvt_pk_bf16_f32 v62, v62, v63
	v_cvt_pk_bf16_f32 v63, v64, v65
	v_cvt_pk_bf16_f32 v54, v54, v55
	v_cvt_pk_bf16_f32 v55, v56, v57
	ds_write_b64 v228, v[62:63] offset:26112
	ds_write_b64 v228, v[54:55] offset:26144
	v_pk_mul_f32 v[208:209], v[46:47], v[224:225] op_sel_hi:[1,0]
	v_pk_mul_f32 v[210:211], v[48:49], v[224:225] op_sel_hi:[1,0]
	v_pk_mul_f32 v[212:213], v[38:39], v[224:225] op_sel_hi:[1,0]
	v_pk_mul_f32 v[214:215], v[40:41], v[224:225] op_sel_hi:[1,0]
	v_min_f32_e32 v208, 0x42fc0000, v208
	v_min_f32_e32 v209, 0x42fc0000, v209
	v_min_f32_e32 v210, 0x42fc0000, v210
	v_min_f32_e32 v211, 0x42fc0000, v211
	v_min_f32_e32 v212, 0x42fc0000, v212
	v_min_f32_e32 v213, 0x42fc0000, v213
	v_min_f32_e32 v214, 0x42fc0000, v214
	v_min_f32_e32 v215, 0x42fc0000, v215
	v_exp_f32_e32 v208, v208
	v_exp_f32_e32 v209, v209
	v_exp_f32_e32 v210, v210
	v_exp_f32_e32 v211, v211
	v_exp_f32_e32 v212, v212
	v_exp_f32_e32 v213, v213
	v_exp_f32_e32 v214, v214
	v_exp_f32_e32 v215, v215
	v_pk_add_f32 v[208:209], v[208:209], v[226:227] op_sel_hi:[1,0]
	v_pk_add_f32 v[210:211], v[210:211], v[226:227] op_sel_hi:[1,0]
	v_pk_add_f32 v[212:213], v[212:213], v[226:227] op_sel_hi:[1,0]
	v_pk_add_f32 v[214:215], v[214:215], v[226:227] op_sel_hi:[1,0]
	v_rcp_f32_e32 v216, v208
	v_rcp_f32_e32 v217, v209
	v_rcp_f32_e32 v218, v210
	v_rcp_f32_e32 v219, v211
	v_rcp_f32_e32 v220, v212
	v_rcp_f32_e32 v221, v213
	v_rcp_f32_e32 v222, v214
	v_rcp_f32_e32 v223, v215
	v_pk_fma_f32 v[208:209], v[208:209], v[216:217], v[226:227] op_sel_hi:[1,1,0] neg_lo:[1,0,0] neg_hi:[1,0,0]
	v_pk_fma_f32 v[210:211], v[210:211], v[218:219], v[226:227] op_sel_hi:[1,1,0] neg_lo:[1,0,0] neg_hi:[1,0,0]
	v_pk_fma_f32 v[212:213], v[212:213], v[220:221], v[226:227] op_sel_hi:[1,1,0] neg_lo:[1,0,0] neg_hi:[1,0,0]
	v_pk_fma_f32 v[214:215], v[214:215], v[222:223], v[226:227] op_sel_hi:[1,1,0] neg_lo:[1,0,0] neg_hi:[1,0,0]
	v_pk_fma_f32 v[216:217], v[208:209], v[216:217], v[216:217]
	v_pk_fma_f32 v[218:219], v[210:211], v[218:219], v[218:219]
	v_pk_fma_f32 v[220:221], v[212:213], v[220:221], v[220:221]
	v_pk_fma_f32 v[222:223], v[214:215], v[222:223], v[222:223]
	v_pk_mul_f32 v[46:47], v[46:47], v[216:217]
	v_pk_mul_f32 v[48:49], v[48:49], v[218:219]
	v_pk_mul_f32 v[38:39], v[38:39], v[220:221]
	v_pk_mul_f32 v[40:41], v[40:41], v[222:223]
	v_pk_mul_f32 v[46:47], v[46:47], v[42:43]
	v_pk_mul_f32 v[48:49], v[48:49], v[44:45]
	v_pk_mul_f32 v[38:39], v[38:39], v[34:35]
	v_pk_mul_f32 v[40:41], v[40:41], v[36:37]
	v_cvt_pk_bf16_f32 v46, v46, v47
	v_cvt_pk_bf16_f32 v47, v48, v49
	v_cvt_pk_bf16_f32 v38, v38, v39
	v_cvt_pk_bf16_f32 v39, v40, v41
	ds_write_b64 v228, v[46:47] offset:30464
	ds_write_b64 v228, v[38:39] offset:30496
	s_waitcnt lgkmcnt(0)
	s_barrier
; __device__ __forceinline__ void phase_ffn_up(const Params& p, const u16* Wgu, u16* smem, volatile LAS unsigned* vb_) {
;     ...
; #pragma unroll
;     for (int k = 0; k < 8; ++k) {
;       const int c = tid + 512 * k;
;       const int row = c >> 4, ch = c & 15;
;       const uint4 v = *(const uint4*)(smem + row * 136 + ch * 8);
;       *(uint4*)(act + (size_t)(mt * 256 + row) * DFF + nt * 128 + ch * 8) = v;
;     }
;     __syncthreads();
;   }
	s_lshl_b32 s12, s40, 7
	s_ashr_i32 s13, s12, 31
	v_lshl_add_u64 v[38:39], s[12:13], 1, v[166:167]
	s_and_b64 vcc, exec, s[10:11]
	s_mov_b32 s20, s41
	ds_read_b128 v[34:37], v197
	s_add_i32 s49, s39, 0
	v_add_u32_e32 v40, s49, v189
	v_mad_i64_i32 v[40:41], s[12:13], v40, s7, v[38:39]
	s_waitcnt lgkmcnt(0)
	global_store_dwordx4 v[40:41], v[34:37], off
	ds_read_b128 v[34:37], v197 offset:8704
	s_add_i32 s49, s39, 32
	v_add_u32_e32 v40, s49, v189
	v_mad_i64_i32 v[40:41], s[12:13], v40, s7, v[38:39]
	s_waitcnt lgkmcnt(0)
	global_store_dwordx4 v[40:41], v[34:37], off
	ds_read_b128 v[34:37], v197 offset:17408
	s_add_i32 s49, s39, 64
	v_add_u32_e32 v40, s49, v189
	v_mad_i64_i32 v[40:41], s[12:13], v40, s7, v[38:39]
	s_waitcnt lgkmcnt(0)
	global_store_dwordx4 v[40:41], v[34:37], off
	ds_read_b128 v[34:37], v197 offset:26112
	s_add_i32 s49, s39, 96
	v_add_u32_e32 v40, s49, v189
	v_mad_i64_i32 v[40:41], s[12:13], v40, s7, v[38:39]
	s_waitcnt lgkmcnt(0)
	global_store_dwordx4 v[40:41], v[34:37], off
	ds_read_b128 v[34:37], v197 offset:34816
	s_add_i32 s49, s39, 128
	v_add_u32_e32 v40, s49, v189
	v_mad_i64_i32 v[40:41], s[12:13], v40, s7, v[38:39]
	s_waitcnt lgkmcnt(0)
	global_store_dwordx4 v[40:41], v[34:37], off
	ds_read_b128 v[34:37], v197 offset:43520
	s_add_i32 s49, s39, 160
	v_add_u32_e32 v40, s49, v189
	v_mad_i64_i32 v[40:41], s[12:13], v40, s7, v[38:39]
	s_waitcnt lgkmcnt(0)
	global_store_dwordx4 v[40:41], v[34:37], off
	ds_read_b128 v[34:37], v197 offset:52224
	s_add_i32 s49, s39, 192
	v_add_u32_e32 v40, s49, v189
	v_mad_i64_i32 v[40:41], s[12:13], v40, s7, v[38:39]
	s_waitcnt lgkmcnt(0)
	global_store_dwordx4 v[40:41], v[34:37], off
	ds_read_b128 v[34:37], v197 offset:60928
	s_add_i32 s49, s39, 224
	v_add_u32_e32 v40, s49, v189
	v_mad_i64_i32 v[40:41], s[12:13], v40, s7, v[38:39]
	s_waitcnt lgkmcnt(0)
	global_store_dwordx4 v[40:41], v[34:37], off
	s_mov_b64 s[12:13], -1
	s_barrier
	s_cbranch_vccz .LBB0_598
